# attention-phase prologue: gain-bound loads issued together (one wait instead of two serialized round trips)
# speedup vs baseline: 1.0000x; 1.0000x over previous
.LBB0_1164:
	s_or_b64 exec, exec, s[0:1]
	v_lshlrev_b32_e32 v148, 2, v158
	s_waitcnt lgkmcnt(0)
	s_barrier
	global_load_dword v1, v148, s[24:25]
	v_cmp_gt_u32_e32 vcc, 32, v158
	v_mov_b32_e32 v2, 0
	v_mov_b32_e32 v3, 0
	global_load_dword v0, v148, s[26:27]
	s_and_saveexec_b64 s[0:1], vcc
	s_cbranch_execz .LBB0_1168
	v_lshl_add_u64 v[4:5], s[24:25], 0, v[148:149]
	global_load_dword v70, v[4:5], off offset:256
	v_lshl_add_u64 v[4:5], s[26:27], 0, v[148:149]
	global_load_dword v2, v[4:5], off offset:256
	s_waitcnt vmcnt(0)
	v_and_b32_e32 v3, 0x7fffffff, v70
	v_and_b32_e32 v2, 0x7fffffff, v2
